# scan loader waves: dead zero-fill of the masked stream registers removed (lanes outside the mask never store them), on top of the hoisted select
# baseline (speedup 1.0000x reference)
; #define LAS __attribute__((address_space(3)))
; __device__ __forceinline__ void scan_load_chunk(LAS unsigned char* slot, const float* Wd, const float* V, const bf16_t* RKKB, int p, int rg, int s0, int lt) {
;     ...
;     for (int j = 0; j < 2; ++j) { const int idx = lt + 256 * j, st = idx >> 4, part = idx & 15; r[j] = *(const u32x4*)(Wd + (base + st) * 64 + part * 4); }
; #pragma unroll
;     for (int j = 2; j < 6; ++j) { const int k = lt + 256 * (j - 2), st = k >> 5, rem = k & 31, q = rem >> 3, part = rem & 7; r[j] = *(const u32x4*)(RKKB + ((base + st) * 4 + q) * 64 + part * 8); }
;     if (lt < 128) { const int st = lt >> 2, hf = lt & 3; r[6] = *(const u32x4*)(V + (base + st) * 64 + rg * 16 + hf * 4); }
; #pragma unroll
;     for (int j = 0; j < 2; ++j) { const int idx = lt + 256 * j, st = idx >> 4, part = idx & 15; *(LAS u32x4*)(slot + st * SCAN_STEP_B + part * 16) = r[j]; }
; #pragma unroll
;     for (int j = 2; j < 6; ++j) { const int k = lt + 256 * (j - 2), st = k >> 5, rem = k & 31, q = rem >> 3, part = rem & 7; const u32x4 w = r[j];
;         const int Q = (q == 0) ? 4 : (q == 1) ? 2 : (q == 2) ? 3 : 1;
.Lscan_ldprime:
	v_mov_b32_e32 v136, 0x400
	v_cmp_lt_i32_e32 vcc, 0, v69
	v_mov_b32_e32 v137, 0x200
	v_cndmask_b32_e32 v136, v136, v70, vcc
	v_cmp_eq_u32_e32 vcc, 1, v69
	s_nop 0
	v_cndmask_b32_e32 v136, v136, v137, vcc
	v_lshl_add_u64 v[134:135], v[58:59], 0, s[14:15]
	global_load_dwordx4 v[130:133], v[134:135], off
	v_lshl_add_u64 v[134:135], v[56:57], 0, s[14:15]
	global_load_dwordx4 v[126:129], v[134:135], off
	v_lshl_add_u64 v[134:135], v[54:55], 0, s[14:15]
	global_load_dwordx4 v[122:125], v[134:135], off
	v_lshl_add_u64 v[134:135], v[52:53], 0, s[14:15]
	global_load_dwordx4 v[118:121], v[134:135], off
	v_lshl_add_u64 v[134:135], v[50:51], 0, s[14:15]
	global_load_dwordx4 v[114:117], v[134:135], off
	v_lshl_add_u64 v[134:135], v[48:49], 0, s[14:15]
	global_load_dwordx4 v[106:109], v[134:135], off
	s_and_saveexec_b64 s[18:19], s[12:13]
	v_lshl_add_u64 v[134:135], v[46:47], 0, s[14:15]
	global_load_dwordx4 v[110:113], v[134:135], off
	s_or_b64 exec, exec, s[18:19]

; __device__ __forceinline__ void scan_load_chunk(LAS unsigned char* slot, const float* Wd, const float* V, const bf16_t* RKKB, int p, int rg, int s0, int lt) {
;     ...
;     for (int j = 0; j < 2; ++j) { const int idx = lt + 256 * j, st = idx >> 4, part = idx & 15; r[j] = *(const u32x4*)(Wd + (base + st) * 64 + part * 4); }
; #pragma unroll
;     for (int j = 2; j < 6; ++j) { const int k = lt + 256 * (j - 2), st = k >> 5, rem = k & 31, q = rem >> 3, part = rem & 7; r[j] = *(const u32x4*)(RKKB + ((base + st) * 4 + q) * 64 + part * 8); }
;     if (lt < 128) { const int st = lt >> 2, hf = lt & 3; r[6] = *(const u32x4*)(V + (base + st) * 64 + rg * 16 + hf * 4); }
; __device__ __forceinline__ void rwkv_scan_unit(LAS unsigned char* lds, const float* Wd, const float* V, const bf16_t* RKKB, float* Yraw, int p, int rg, int tid) {
;     ...
;         if (wave >= 4) { if (c + 2 < NCH) scan_load_chunk(lds + ((c + 2) % 3) * SCAN_SLOT_B, Wd, V, RKKB, p, rg, (c + 2) * SCAN_CH, tid - 256); }
.LBB0_345:
	s_add_i32 s22, s22, 1
	s_mov_b64 s[18:19], 0x2000
	s_mov_b64 s[20:21], 0x4000
	v_mov_b64_e32 v[2:3], v[6:7]
	v_lshl_add_u64 v[46:47], v[46:47], 0, s[18:19]
	v_lshl_add_u64 v[48:49], v[48:49], 0, s[20:21]
	v_lshl_add_u64 v[50:51], v[50:51], 0, s[20:21]
	v_lshl_add_u64 v[52:53], v[52:53], 0, s[20:21]
	v_lshl_add_u64 v[54:55], v[54:55], 0, s[20:21]
	v_lshl_add_u64 v[56:57], v[56:57], 0, s[18:19]
	v_lshl_add_u64 v[58:59], v[58:59], 0, s[18:19]
	s_mov_b64 s[68:69], 0x2000
	v_lshl_add_u64 v[60:61], v[60:61], 0, s[18:19]
	s_cmpk_gt_u32 s22, 0x7d
	s_cbranch_scc1 .Lscan_ld_skip
	v_lshl_add_u64 v[134:135], v[58:59], 0, s[14:15]
	global_load_dwordx4 v[130:133], v[134:135], off
	v_lshl_add_u64 v[134:135], v[56:57], 0, s[14:15]
	global_load_dwordx4 v[126:129], v[134:135], off
	v_lshl_add_u64 v[134:135], v[54:55], 0, s[14:15]
	global_load_dwordx4 v[122:125], v[134:135], off
	v_lshl_add_u64 v[134:135], v[52:53], 0, s[14:15]
	global_load_dwordx4 v[118:121], v[134:135], off
	v_lshl_add_u64 v[134:135], v[50:51], 0, s[14:15]
	global_load_dwordx4 v[114:117], v[134:135], off
	v_lshl_add_u64 v[134:135], v[48:49], 0, s[14:15]
	global_load_dwordx4 v[106:109], v[134:135], off
	s_and_saveexec_b64 s[18:19], s[12:13]
	v_lshl_add_u64 v[134:135], v[46:47], 0, s[14:15]
	global_load_dwordx4 v[110:113], v[134:135], off
	s_or_b64 exec, exec, s[18:19]
